# nt policy on MERGE epilogue gate and Mg loads in addition to XN1 rows
# baseline (speedup 1.0000x reference)
;     __device__ __forceinline__ void operator()(const f32x4 (&acc)[2][2][4][2], const pg8::Unit& u, int wr, int wc, int fr, int fq) const {
;         const int br = u.pn >> 3, pn = u.pn & 7, pm = u.pm - br * 65;
;         const int row0 = pm * 256 + wr * 64 + fr, col0 = pn * 256 + wc * 32 + 8 * fq;
; #pragma unroll
;         for (int ai = 0; ai < 2; ++ai) { u32x4 gw[4][2], ow[4][2];
; #pragma unroll
;             for (int m = 0; m < 4; ++m)
; #pragma unroll
;                 for (int bj = 0; bj < 2; ++bj) { const int row = row0 + ai * 128 + m * 16, col = col0 + bj * 128;
;                     gw[m][bj] = *(const u32x4*)(Pg + (size_t)row * LDP + br * 2048 + col);
;                     if (br) ow[m][bj] = *(const u32x4*)(Mg + (size_t)row * DM + col); else ow[m][bj] = (u32x4){0u, 0u, 0u, 0u}; }
.LBB0_961:
	s_ashr_i32 s4, s67, 3
	s_mul_i32 s5, s4, 0xffffffbf
	s_add_i32 s5, s5, s28
	v_lshl_add_u32 v212, s5, 8, v201
	s_lshl_b32 s5, s67, 8
	s_and_b32 s5, s5, 0x700
	s_lshl_b32 s4, s4, 11
	v_or_b32_e32 v0, s5, v243
	s_ashr_i32 s5, s4, 31
	s_cmp_gt_u32 s67, 7
	s_cselect_b64 s[28:29], -1, 0
	s_lshl_b64 s[4:5], s[4:5], 1
	s_add_u32 s26, s62, s4
	s_addc_u32 s27, s63, s5
	v_mov_b64_e32 v[130:131], s[26:27]
	v_mad_i64_i32 v[130:131], s[4:5], v212, s3, v[130:131]
	v_lshlrev_b32_e32 v0, 1, v0
	v_lshl_add_u64 v[130:131], v[130:131], 0, v[0:1]
	global_load_dwordx4 v[186:189], v[130:131], off nt
	v_ashrrev_i32_e32 v213, 31, v212
	v_lshlrev_b64 v[132:133], 12, v[212:213]
	s_cmp_lt_u32 s67, 8
	v_lshl_add_u64 v[220:221], s[10:11], 0, v[132:133]
	v_mov_b32_e32 v158, 0
	v_mov_b32_e32 v190, 0
	v_mov_b32_e32 v191, 0
	v_mov_b32_e32 v192, 0
	v_mov_b32_e32 v193, 0
	s_movk_i32 s68, 0x4000
	s_movk_i32 s69, 0x3000
	s_movk_i32 s70, 0x1dff
	s_movk_i32 s71, 0x1000
	s_cbranch_scc1 .LBB0_963
	v_lshl_add_u64 v[132:133], v[220:221], 0, v[0:1]
	global_load_dwordx4 v[190:193], v[132:133], off nt
.LBB0_963:
	global_load_dwordx4 v[178:181], v[130:131], off offset:256 nt
	v_cndmask_b32_e64 v130, 0, 1, s[28:29]
	v_cmp_ne_u32_e64 s[4:5], 1, v130
	s_andn2_b64 vcc, exec, s[28:29]
	v_mov_b32_e32 v159, 0
	v_mov_b32_e32 v160, 0
	v_mov_b32_e32 v161, 0
	s_cbranch_vccnz .LBB0_965
	v_lshl_add_u64 v[130:131], v[220:221], 0, v[0:1]
	global_load_dwordx4 v[158:161], v[130:131], off offset:256 nt
.LBB0_965:
	v_or_b32_e32 v132, 16, v212
	v_mov_b64_e32 v[130:131], s[26:27]
	v_mad_i64_i32 v[130:131], s[28:29], v132, s3, v[130:131]
	v_lshl_add_u64 v[130:131], v[130:131], 0, v[0:1]
	global_load_dwordx4 v[174:177], v[130:131], off nt
	v_ashrrev_i32_e32 v133, 31, v132
	v_lshlrev_b64 v[132:133], 12, v[132:133]
	v_lshl_add_u64 v[218:219], s[10:11], 0, v[132:133]
	v_mov_b32_e32 v142, 0
	s_and_b64 vcc, exec, s[4:5]
	v_mov_b32_e32 v182, 0
	v_mov_b32_e32 v183, 0
	v_mov_b32_e32 v184, 0
	v_mov_b32_e32 v185, 0
	v_readlane_b32 s72, v254, 19
	s_movk_i32 s74, 0x2000
	v_readlane_b32 s73, v254, 20
	s_cbranch_vccnz .LBB0_967
	v_lshl_add_u64 v[132:133], v[218:219], 0, v[0:1]
	global_load_dwordx4 v[182:185], v[132:133], off nt
.LBB0_967:
	global_load_dwordx4 v[166:169], v[130:131], off offset:256 nt
	s_and_b64 vcc, exec, s[4:5]
	v_mov_b32_e32 v143, 0
	v_mov_b32_e32 v144, 0
	v_mov_b32_e32 v145, 0
	s_cbranch_vccnz .LBB0_969
	v_lshl_add_u64 v[130:131], v[218:219], 0, v[0:1]
	global_load_dwordx4 v[142:145], v[130:131], off offset:256 nt
.LBB0_969:
	v_or_b32_e32 v132, 32, v212
	v_mov_b64_e32 v[130:131], s[26:27]
	v_mad_i64_i32 v[130:131], s[28:29], v132, s3, v[130:131]
	v_lshl_add_u64 v[130:131], v[130:131], 0, v[0:1]
	global_load_dwordx4 v[162:165], v[130:131], off nt
	v_ashrrev_i32_e32 v133, 31, v132
	v_lshlrev_b64 v[132:133], 12, v[132:133]
	v_lshl_add_u64 v[216:217], s[10:11], 0, v[132:133]
	v_mov_b32_e32 v138, 0
	s_and_b64 vcc, exec, s[4:5]
	v_mov_b32_e32 v170, 0
	v_mov_b32_e32 v171, 0
	v_mov_b32_e32 v172, 0
	v_mov_b32_e32 v173, 0
	s_cbranch_vccnz .LBB0_971
	v_lshl_add_u64 v[132:133], v[216:217], 0, v[0:1]
	global_load_dwordx4 v[170:173], v[132:133], off nt
.LBB0_971:
	global_load_dwordx4 v[150:153], v[130:131], off offset:256 nt
	s_and_b64 vcc, exec, s[4:5]
	v_mov_b32_e32 v139, 0
	v_mov_b32_e32 v140, 0
	v_mov_b32_e32 v141, 0
	s_cbranch_vccnz .LBB0_973
	v_lshl_add_u64 v[130:131], v[216:217], 0, v[0:1]
	global_load_dwordx4 v[138:141], v[130:131], off offset:256 nt
.LBB0_973:
	v_or_b32_e32 v130, 48, v212
	v_mov_b64_e32 v[132:133], s[26:27]
	v_mad_i64_i32 v[132:133], s[28:29], v130, s3, v[132:133]
	v_lshl_add_u64 v[132:133], v[132:133], 0, v[0:1]
	global_load_dwordx4 v[146:149], v[132:133], off nt
	v_ashrrev_i32_e32 v131, 31, v130
	v_lshlrev_b64 v[130:131], 12, v[130:131]
	v_lshl_add_u64 v[214:215], s[10:11], 0, v[130:131]
	v_mov_b32_e32 v130, 0
	s_and_b64 vcc, exec, s[4:5]
	v_mov_b32_e32 v154, 0
	v_mov_b32_e32 v155, 0
	v_mov_b32_e32 v156, 0
	v_mov_b32_e32 v157, 0
	s_cbranch_vccnz .LBB0_975
	v_lshl_add_u64 v[134:135], v[214:215], 0, v[0:1]
	global_load_dwordx4 v[154:157], v[134:135], off nt
.LBB0_975:
	s_nop 0
	global_load_dwordx4 v[134:137], v[132:133], off offset:256 nt
	s_and_b64 vcc, exec, s[4:5]
	v_mov_b32_e32 v131, 0
	v_mov_b32_e32 v132, 0
	v_mov_b32_e32 v133, 0
	s_cbranch_vccnz .LBB0_977
	v_lshl_add_u64 v[130:131], v[214:215], 0, v[0:1]
	global_load_dwordx4 v[130:133], v[130:131], off offset:256 nt
; __device__ __forceinline__ unsigned pk2(float lo, float hi) { unsigned r; asm volatile("v_cvt_pk_bf16_f32 %0, %1, %2" : "=v"(r) : "v"(lo), "v"(hi)); return r; }
;     __device__ __forceinline__ void operator()(const f32x4 (&acc)[2][2][4][2], const pg8::Unit& u, int wr, int wc, int fr, int fq) const {
;     ...
;             for (int m = 0; m < 4; ++m)
; #pragma unroll
;                 for (int bj = 0; bj < 2; ++bj) { const int row = row0 + ai * 128 + m * 16, col = col0 + bj * 128;
;                     const f32x4 v0 = acc[ai][bj][m][0], v1 = acc[ai][bj][m][1]; float r[8];
; #pragma unroll
;                     for (int e = 0; e < 4; ++e) { const float a0 = e < 2 ? v0[2 * e] : v1[2 * e - 4], a1 = e < 2 ? v0[2 * e + 1] : v1[2 * e - 3];
;                         r[2 * e] = __uint_as_float(ow[m][bj][e] << 16) + __uint_as_float(gw[m][bj][e] << 16) * a0;
;                         r[2 * e + 1] = __uint_as_float(ow[m][bj][e] & 0xffff0000u) + __uint_as_float(gw[m][bj][e] & 0xffff0000u) * a1; }
;                     u32x4 w; w.x = pk2(r[0], r[1]); w.y = pk2(r[2], r[3]); w.z = pk2(r[4], r[5]); w.w = pk2(r[6], r[7]);
;                     *(u32x4*)(Mg + (size_t)row * DM + col) = w; } }
.LBB0_977:
	s_waitcnt vmcnt(0)
	v_lshlrev_b32_e32 v213, 16, v190
	v_lshlrev_b32_e32 v230, 16, v186
	v_fmac_f32_e32 v213, v126, v230
	v_and_b32_e32 v126, 0xffff0000, v190
	v_and_b32_e32 v186, 0xffff0000, v186
	v_fmac_f32_e32 v126, v127, v186
	v_lshlrev_b32_e32 v127, 16, v191
	v_lshlrev_b32_e32 v186, 16, v187
	v_fmac_f32_e32 v127, v128, v186
	v_and_b32_e32 v128, 0xffff0000, v191
	v_and_b32_e32 v186, 0xffff0000, v187
	v_fmac_f32_e32 v128, v129, v186
	v_lshlrev_b32_e32 v129, 16, v192
	v_lshlrev_b32_e32 v186, 16, v188
	v_fmac_f32_e32 v129, v118, v186
	v_and_b32_e32 v186, 0xffff0000, v192
	v_and_b32_e32 v118, 0xffff0000, v188
	v_fmac_f32_e32 v186, v119, v118
	v_lshlrev_b32_e32 v187, 16, v193
	v_lshlrev_b32_e32 v118, 16, v189
	v_fmac_f32_e32 v187, v120, v118
	v_and_b32_e32 v188, 0xffff0000, v193
	v_and_b32_e32 v118, 0xffff0000, v189
	v_fmac_f32_e32 v188, v121, v118
	v_cvt_pk_bf16_f32 v118, v213, v126
	v_cvt_pk_bf16_f32 v119, v127, v128
	v_lshl_add_u64 v[126:127], v[220:221], 0, v[0:1]
	v_cvt_pk_bf16_f32 v120, v129, v186
	v_cvt_pk_bf16_f32 v121, v187, v188
	global_store_dwordx4 v[126:127], v[118:121], off
	s_and_b64 vcc, exec, s[4:5]
	v_mov_b32_e32 v128, 0
	v_lshlrev_b32_e32 v118, 16, v158
	v_lshlrev_b32_e32 v119, 16, v178
	v_fmac_f32_e32 v118, v122, v119
	v_and_b32_e32 v119, 0xffff0000, v158
	v_and_b32_e32 v120, 0xffff0000, v178
	v_fmac_f32_e32 v119, v123, v120
	v_lshlrev_b32_e32 v120, 16, v159
	v_lshlrev_b32_e32 v121, 16, v179
	v_fmac_f32_e32 v120, v124, v121
	v_and_b32_e32 v121, 0xffff0000, v159
	v_and_b32_e32 v122, 0xffff0000, v179
	v_fmac_f32_e32 v121, v125, v122
	v_lshlrev_b32_e32 v122, 16, v160
	v_lshlrev_b32_e32 v123, 16, v180
	v_fmac_f32_e32 v122, v114, v123
	v_and_b32_e32 v123, 0xffff0000, v160
	v_and_b32_e32 v114, 0xffff0000, v180
	v_fmac_f32_e32 v123, v115, v114
	v_lshlrev_b32_e32 v124, 16, v161
	v_lshlrev_b32_e32 v114, 16, v181
	v_fmac_f32_e32 v124, v116, v114
	v_and_b32_e32 v125, 0xffff0000, v161
	v_and_b32_e32 v114, 0xffff0000, v181
	v_fmac_f32_e32 v125, v117, v114
	v_cvt_pk_bf16_f32 v114, v118, v119
	v_cvt_pk_bf16_f32 v115, v120, v121
	v_cvt_pk_bf16_f32 v116, v122, v123
	v_cvt_pk_bf16_f32 v117, v124, v125
	global_store_dwordx4 v[126:127], v[114:117], off offset:256
	v_mov_b32_e32 v126, 0
	v_mov_b32_e32 v127, 0
	v_lshlrev_b32_e32 v114, 16, v182
	v_lshlrev_b32_e32 v115, 16, v174
	v_fmac_f32_e32 v114, v110, v115
	v_and_b32_e32 v110, 0xffff0000, v182
	v_and_b32_e32 v115, 0xffff0000, v174
	v_fmac_f32_e32 v110, v111, v115
	v_lshlrev_b32_e32 v111, 16, v183
	v_lshlrev_b32_e32 v115, 16, v175
	v_fmac_f32_e32 v111, v112, v115
	v_and_b32_e32 v112, 0xffff0000, v183
	v_and_b32_e32 v115, 0xffff0000, v175
	v_fmac_f32_e32 v112, v113, v115
	v_lshlrev_b32_e32 v113, 16, v184
	v_lshlrev_b32_e32 v115, 16, v176
	v_fmac_f32_e32 v113, v102, v115
	v_and_b32_e32 v115, 0xffff0000, v184
	v_and_b32_e32 v102, 0xffff0000, v176
	v_fmac_f32_e32 v115, v103, v102
	v_lshlrev_b32_e32 v116, 16, v185
	v_lshlrev_b32_e32 v102, 16, v177
	v_fmac_f32_e32 v116, v104, v102
	v_and_b32_e32 v117, 0xffff0000, v185
	v_and_b32_e32 v102, 0xffff0000, v177
	v_fmac_f32_e32 v117, v105, v102
	v_cvt_pk_bf16_f32 v102, v114, v110
	v_cvt_pk_bf16_f32 v103, v111, v112
	v_lshl_add_u64 v[110:111], v[218:219], 0, v[0:1]
	v_cvt_pk_bf16_f32 v104, v113, v115
	v_cvt_pk_bf16_f32 v105, v116, v117
	global_store_dwordx4 v[110:111], v[102:105], off
	v_mov_b32_e32 v129, 0
	s_nop 0
	v_lshlrev_b32_e32 v102, 16, v142
	v_lshlrev_b32_e32 v103, 16, v166
	v_fmac_f32_e32 v102, v106, v103
	v_and_b32_e32 v103, 0xffff0000, v142
	v_and_b32_e32 v104, 0xffff0000, v166
	v_fmac_f32_e32 v103, v107, v104
	v_lshlrev_b32_e32 v104, 16, v143
	v_lshlrev_b32_e32 v105, 16, v167
	v_fmac_f32_e32 v104, v108, v105
	v_and_b32_e32 v105, 0xffff0000, v143
	v_and_b32_e32 v106, 0xffff0000, v167
	v_fmac_f32_e32 v105, v109, v106
	v_lshlrev_b32_e32 v106, 16, v144
	v_lshlrev_b32_e32 v107, 16, v168
	v_fmac_f32_e32 v106, v98, v107
	v_and_b32_e32 v107, 0xffff0000, v144
	v_and_b32_e32 v98, 0xffff0000, v168
	v_fmac_f32_e32 v107, v99, v98
	v_lshlrev_b32_e32 v108, 16, v145
	v_lshlrev_b32_e32 v98, 16, v169
	v_fmac_f32_e32 v108, v100, v98
	v_and_b32_e32 v109, 0xffff0000, v145
	v_and_b32_e32 v98, 0xffff0000, v169
	v_fmac_f32_e32 v109, v101, v98
	v_cvt_pk_bf16_f32 v98, v102, v103
	v_cvt_pk_bf16_f32 v99, v104, v105
	v_cvt_pk_bf16_f32 v100, v106, v107
	v_cvt_pk_bf16_f32 v101, v108, v109
	global_store_dwordx4 v[110:111], v[98:101], off offset:256
	s_nop 1
	v_lshlrev_b32_e32 v98, 16, v170
	v_lshlrev_b32_e32 v99, 16, v162
	v_fmac_f32_e32 v98, v94, v99
	v_and_b32_e32 v94, 0xffff0000, v170
	v_and_b32_e32 v99, 0xffff0000, v162
	v_fmac_f32_e32 v94, v95, v99
	v_lshlrev_b32_e32 v95, 16, v171
	v_lshlrev_b32_e32 v99, 16, v163
	v_fmac_f32_e32 v95, v96, v99
	v_and_b32_e32 v96, 0xffff0000, v171
	v_and_b32_e32 v99, 0xffff0000, v163
	v_fmac_f32_e32 v96, v97, v99
	v_lshlrev_b32_e32 v97, 16, v172
	v_lshlrev_b32_e32 v99, 16, v164
	v_fmac_f32_e32 v97, v86, v99
	v_and_b32_e32 v99, 0xffff0000, v172
	v_and_b32_e32 v86, 0xffff0000, v164
	v_fmac_f32_e32 v99, v87, v86
	v_lshlrev_b32_e32 v100, 16, v173
	v_lshlrev_b32_e32 v86, 16, v165
	v_fmac_f32_e32 v100, v88, v86
	v_and_b32_e32 v101, 0xffff0000, v173
	v_and_b32_e32 v86, 0xffff0000, v165
	v_fmac_f32_e32 v101, v89, v86
	v_cvt_pk_bf16_f32 v86, v98, v94
	v_cvt_pk_bf16_f32 v87, v95, v96
	v_lshl_add_u64 v[94:95], v[216:217], 0, v[0:1]
	v_cvt_pk_bf16_f32 v88, v97, v99
	v_cvt_pk_bf16_f32 v89, v100, v101
	global_store_dwordx4 v[94:95], v[86:89], off
	v_mov_b32_e32 v98, 0
	s_nop 0
	v_lshlrev_b32_e32 v86, 16, v138
	v_lshlrev_b32_e32 v87, 16, v150
	v_fmac_f32_e32 v86, v90, v87
	v_and_b32_e32 v87, 0xffff0000, v138
	v_and_b32_e32 v88, 0xffff0000, v150
; __device__ __forceinline__ unsigned pk2(float lo, float hi) { unsigned r; asm volatile("v_cvt_pk_bf16_f32 %0, %1, %2" : "=v"(r) : "v"(lo), "v"(hi)); return r; }
;     __device__ __forceinline__ void operator()(const f32x4 (&acc)[2][2][4][2], const pg8::Unit& u, int wr, int wc, int fr, int fq) const {
;     ...
;         for (int ai = 0; ai < 2; ++ai) { u32x4 gw[4][2], ow[4][2];
; #pragma unroll
;             for (int m = 0; m < 4; ++m)
; #pragma unroll
;                 for (int bj = 0; bj < 2; ++bj) { const int row = row0 + ai * 128 + m * 16, col = col0 + bj * 128;
;                     gw[m][bj] = *(const u32x4*)(Pg + (size_t)row * LDP + br * 2048 + col);
;                     if (br) ow[m][bj] = *(const u32x4*)(Mg + (size_t)row * DM + col); else ow[m][bj] = (u32x4){0u, 0u, 0u, 0u}; }
; #pragma unroll
;             for (int m = 0; m < 4; ++m)
; #pragma unroll
;                 for (int bj = 0; bj < 2; ++bj) { const int row = row0 + ai * 128 + m * 16, col = col0 + bj * 128;
;                     const f32x4 v0 = acc[ai][bj][m][0], v1 = acc[ai][bj][m][1]; float r[8];
; #pragma unroll
;                     for (int e = 0; e < 4; ++e) { const float a0 = e < 2 ? v0[2 * e] : v1[2 * e - 4], a1 = e < 2 ? v0[2 * e + 1] : v1[2 * e - 3];
;                         r[2 * e] = __uint_as_float(ow[m][bj][e] << 16) + __uint_as_float(gw[m][bj][e] << 16) * a0;
;                         r[2 * e + 1] = __uint_as_float(ow[m][bj][e] & 0xffff0000u) + __uint_as_float(gw[m][bj][e] & 0xffff0000u) * a1; }
;                     u32x4 w; w.x = pk2(r[0], r[1]); w.y = pk2(r[2], r[3]); w.z = pk2(r[4], r[5]); w.w = pk2(r[6], r[7]);
;                     *(u32x4*)(Mg + (size_t)row * DM + col) = w; } }
	v_fmac_f32_e32 v87, v91, v88
	v_lshlrev_b32_e32 v88, 16, v139
	v_lshlrev_b32_e32 v89, 16, v151
	v_fmac_f32_e32 v88, v92, v89
	v_and_b32_e32 v89, 0xffff0000, v139
	v_and_b32_e32 v90, 0xffff0000, v151
	v_fmac_f32_e32 v89, v93, v90
	v_lshlrev_b32_e32 v90, 16, v140
	v_lshlrev_b32_e32 v91, 16, v152
	v_fmac_f32_e32 v90, v82, v91
	v_and_b32_e32 v91, 0xffff0000, v140
	v_and_b32_e32 v82, 0xffff0000, v152
	v_fmac_f32_e32 v91, v83, v82
	v_lshlrev_b32_e32 v92, 16, v141
	v_lshlrev_b32_e32 v82, 16, v153
	v_fmac_f32_e32 v92, v84, v82
	v_and_b32_e32 v93, 0xffff0000, v141
	v_and_b32_e32 v82, 0xffff0000, v153
	v_fmac_f32_e32 v93, v85, v82
	v_cvt_pk_bf16_f32 v82, v86, v87
	v_cvt_pk_bf16_f32 v83, v88, v89
	v_cvt_pk_bf16_f32 v84, v90, v91
	v_cvt_pk_bf16_f32 v85, v92, v93
	global_store_dwordx4 v[94:95], v[82:85], off offset:256
	s_nop 1
	v_lshlrev_b32_e32 v82, 16, v154
	v_lshlrev_b32_e32 v83, 16, v146
	v_fmac_f32_e32 v82, v78, v83
	v_and_b32_e32 v78, 0xffff0000, v154
	v_and_b32_e32 v83, 0xffff0000, v146
	v_fmac_f32_e32 v78, v79, v83
	v_lshlrev_b32_e32 v79, 16, v155
	v_lshlrev_b32_e32 v83, 16, v147
	v_fmac_f32_e32 v79, v80, v83
	v_and_b32_e32 v80, 0xffff0000, v155
	v_and_b32_e32 v83, 0xffff0000, v147
	v_fmac_f32_e32 v80, v81, v83
	v_lshlrev_b32_e32 v81, 16, v156
	v_lshlrev_b32_e32 v83, 16, v148
	v_fmac_f32_e32 v81, v70, v83
	v_and_b32_e32 v83, 0xffff0000, v156
	v_and_b32_e32 v70, 0xffff0000, v148
	v_fmac_f32_e32 v83, v71, v70
	v_lshlrev_b32_e32 v84, 16, v157
	v_lshlrev_b32_e32 v70, 16, v149
	v_fmac_f32_e32 v84, v72, v70
	v_and_b32_e32 v85, 0xffff0000, v157
	v_and_b32_e32 v70, 0xffff0000, v149
	v_fmac_f32_e32 v85, v73, v70
	v_cvt_pk_bf16_f32 v70, v82, v78
	v_cvt_pk_bf16_f32 v71, v79, v80
	v_lshl_add_u64 v[78:79], v[214:215], 0, v[0:1]
	v_cvt_pk_bf16_f32 v72, v81, v83
	v_cvt_pk_bf16_f32 v73, v84, v85
	global_store_dwordx4 v[78:79], v[70:73], off
	s_nop 1
	v_lshlrev_b32_e32 v70, 16, v130
	v_lshlrev_b32_e32 v71, 16, v134
	v_fmac_f32_e32 v70, v74, v71
	v_and_b32_e32 v71, 0xffff0000, v130
	v_and_b32_e32 v72, 0xffff0000, v134
	v_fmac_f32_e32 v71, v75, v72
	v_lshlrev_b32_e32 v72, 16, v131
	v_lshlrev_b32_e32 v73, 16, v135
	v_fmac_f32_e32 v72, v76, v73
	v_and_b32_e32 v73, 0xffff0000, v131
	v_and_b32_e32 v74, 0xffff0000, v135
	v_fmac_f32_e32 v73, v77, v74
	v_lshlrev_b32_e32 v74, 16, v132
	v_lshlrev_b32_e32 v75, 16, v136
	v_fmac_f32_e32 v74, v66, v75
	v_and_b32_e32 v66, 0xffff0000, v132
	v_and_b32_e32 v75, 0xffff0000, v136
	v_fmac_f32_e32 v66, v67, v75
	v_lshlrev_b32_e32 v67, 16, v133
	v_lshlrev_b32_e32 v75, 16, v137
	v_fmac_f32_e32 v67, v68, v75
	v_and_b32_e32 v75, 0xffff0000, v133
	v_and_b32_e32 v68, 0xffff0000, v137
	v_fmac_f32_e32 v75, v69, v68
	v_cvt_pk_bf16_f32 v68, v70, v71
	v_cvt_pk_bf16_f32 v69, v72, v73
	v_cvt_pk_bf16_f32 v70, v74, v66
	v_cvt_pk_bf16_f32 v71, v67, v75
	v_add_u32_e32 v72, 0x80, v212
	v_mov_b64_e32 v[66:67], s[26:27]
	v_mad_i64_i32 v[66:67], s[28:29], v72, s3, v[66:67]
	v_lshl_add_u64 v[66:67], v[66:67], 0, v[0:1]
	global_load_dwordx4 v[122:125], v[66:67], off nt
	v_ashrrev_i32_e32 v73, 31, v72
	global_store_dwordx4 v[78:79], v[68:71], off offset:256
	s_nop 1
	v_lshlrev_b64 v[68:69], 12, v[72:73]
	v_lshl_add_u64 v[136:137], s[10:11], 0, v[68:69]
	s_cbranch_vccnz .LBB0_979
	v_lshl_add_u64 v[68:69], v[136:137], 0, v[0:1]
	global_load_dwordx4 v[126:129], v[68:69], off nt
.LBB0_979:
	global_load_dwordx4 v[114:117], v[66:67], off offset:256 nt
	s_and_b64 vcc, exec, s[4:5]
	v_mov_b32_e32 v99, 0
	v_mov_b32_e32 v100, 0
	v_mov_b32_e32 v101, 0
	s_cbranch_vccnz .LBB0_981
	v_lshl_add_u64 v[66:67], v[136:137], 0, v[0:1]
	global_load_dwordx4 v[98:101], v[66:67], off offset:256 nt
.LBB0_981:
	v_add_u32_e32 v68, 0x90, v212
	v_mov_b64_e32 v[66:67], s[26:27]
	v_mad_i64_i32 v[66:67], s[28:29], v68, s3, v[66:67]
	v_lshl_add_u64 v[66:67], v[66:67], 0, v[0:1]
	global_load_dwordx4 v[110:113], v[66:67], off nt
	v_ashrrev_i32_e32 v69, 31, v68
	v_lshlrev_b64 v[68:69], 12, v[68:69]
	v_lshl_add_u64 v[134:135], s[10:11], 0, v[68:69]
	v_mov_b32_e32 v82, 0
	s_and_b64 vcc, exec, s[4:5]
	v_mov_b32_e32 v118, 0
	v_mov_b32_e32 v119, 0
	v_mov_b32_e32 v120, 0
	v_mov_b32_e32 v121, 0
	s_cbranch_vccnz .LBB0_983
	v_lshl_add_u64 v[68:69], v[134:135], 0, v[0:1]
	global_load_dwordx4 v[118:121], v[68:69], off nt
.LBB0_983:
	global_load_dwordx4 v[102:105], v[66:67], off offset:256 nt
	s_and_b64 vcc, exec, s[4:5]
	v_mov_b32_e32 v83, 0
	v_mov_b32_e32 v84, 0
	v_mov_b32_e32 v85, 0
	s_cbranch_vccnz .LBB0_985
	v_lshl_add_u64 v[66:67], v[134:135], 0, v[0:1]
	global_load_dwordx4 v[82:85], v[66:67], off offset:256 nt
.LBB0_985:
	v_add_u32_e32 v68, 0xa0, v212
	v_mov_b64_e32 v[66:67], s[26:27]
	v_mad_i64_i32 v[66:67], s[28:29], v68, s3, v[66:67]
	v_lshl_add_u64 v[66:67], v[66:67], 0, v[0:1]
	global_load_dwordx4 v[94:97], v[66:67], off nt
	v_ashrrev_i32_e32 v69, 31, v68
	v_lshlrev_b64 v[68:69], 12, v[68:69]
	v_lshl_add_u64 v[132:133], s[10:11], 0, v[68:69]
	v_mov_b32_e32 v74, 0
	s_and_b64 vcc, exec, s[4:5]
	v_mov_b32_e32 v106, 0
	v_mov_b32_e32 v107, 0
	v_mov_b32_e32 v108, 0
	v_mov_b32_e32 v109, 0
	s_cbranch_vccnz .LBB0_987
	v_lshl_add_u64 v[68:69], v[132:133], 0, v[0:1]
	global_load_dwordx4 v[106:109], v[68:69], off nt
.LBB0_987:
	global_load_dwordx4 v[86:89], v[66:67], off offset:256 nt
	s_and_b64 vcc, exec, s[4:5]
	v_mov_b32_e32 v75, 0
	v_mov_b32_e32 v76, 0
	v_mov_b32_e32 v77, 0
	s_cbranch_vccnz .LBB0_989
	v_lshl_add_u64 v[66:67], v[132:133], 0, v[0:1]
	global_load_dwordx4 v[74:77], v[66:67], off offset:256 nt
.LBB0_989:
	v_add_u32_e32 v66, 0xb0, v212
	v_mov_b64_e32 v[68:69], s[26:27]
	v_mad_i64_i32 v[68:69], s[26:27], v66, s3, v[68:69]
	v_lshl_add_u64 v[68:69], v[68:69], 0, v[0:1]
	global_load_dwordx4 v[78:81], v[68:69], off nt
	v_ashrrev_i32_e32 v67, 31, v66
	v_lshlrev_b64 v[66:67], 12, v[66:67]
	v_lshl_add_u64 v[130:131], s[10:11], 0, v[66:67]
	v_mov_b32_e32 v66, 0
	s_and_b64 vcc, exec, s[4:5]
	v_mov_b32_e32 v90, 0
	v_mov_b32_e32 v91, 0
	v_mov_b32_e32 v92, 0
	v_mov_b32_e32 v93, 0
	s_cbranch_vccnz .LBB0_991
	v_lshl_add_u64 v[70:71], v[130:131], 0, v[0:1]
	global_load_dwordx4 v[90:93], v[70:71], off nt
.LBB0_991:
	s_nop 0
	global_load_dwordx4 v[70:73], v[68:69], off offset:256 nt
	s_and_b64 vcc, exec, s[4:5]
	v_mov_b32_e32 v67, 0
	v_mov_b32_e32 v68, 0
	v_mov_b32_e32 v69, 0
	s_cbranch_vccnz .LBB0_993
	v_lshl_add_u64 v[66:67], v[130:131], 0, v[0:1]
	global_load_dwordx4 v[66:69], v[66:67], off offset:256 nt
